# cprep T-product loop segment 1: leading 16 LDS operand reads renamed to spare VGPRs and issued together at the block top, counted lgkmcnt waits
# baseline (speedup 1.0000x reference)
.LBB0_653:
	ds_read_b128 v[208:211], v169
	ds_read_b128 v[220:223], v169 offset:16
	ds_read2_b32 v[212:213], v170 offset1:68
	ds_read2_b32 v[224:225], v170 offset0:136 offset1:204
	v_add_u32_e32 v228, 0x400, v170
	ds_read2_b32 v[226:227], v228 offset0:16 offset1:84
	ds_read_b32 v196, v170 offset:1632
	ds_read_b32 v197, v171
	ds_read_b32 v198, v172
	ds_read_b32 v199, v173
	ds_read_b32 v202, v174
	ds_read_b32 v203, v175
	ds_read_b32 v204, v176
	ds_read_b32 v205, v177
	ds_read_b32 v206, v178
	ds_read_b32 v207, v179
	ds_read_b128 v[244:247], v169 offset:128
	s_cmp_lg_u32 s45, 1
	s_cselect_b64 s[42:43], -1, 0
	s_cmp_eq_u32 s45, 1
	s_waitcnt lgkmcnt(15)
	v_cvt_pk_bf16_f32 v30, v208, v209
	v_lshlrev_b32_e32 v18, 16, v30
	v_and_b32_e32 v19, 0xffff0000, v30
	v_pk_add_f32 v[10:11], v[208:209], v[18:19] neg_lo:[0,1] neg_hi:[0,1]
	v_cvt_pk_bf16_f32 v31, v210, v211
	v_cvt_pk_bf16_f32 v34, v10, v11
	v_lshlrev_b32_e32 v10, 16, v31
	v_and_b32_e32 v11, 0xffff0000, v31
	v_pk_add_f32 v[10:11], v[210:211], v[10:11] neg_lo:[0,1] neg_hi:[0,1]
	s_waitcnt lgkmcnt(14)
	v_cvt_pk_bf16_f32 v32, v220, v221
	v_cvt_pk_bf16_f32 v35, v10, v11
	v_lshlrev_b32_e32 v10, 16, v32
	v_and_b32_e32 v11, 0xffff0000, v32
	v_pk_add_f32 v[10:11], v[220:221], v[10:11] neg_lo:[0,1] neg_hi:[0,1]
	v_cvt_pk_bf16_f32 v33, v222, v223
	v_cvt_pk_bf16_f32 v36, v10, v11
	v_lshlrev_b32_e32 v10, 16, v33
	v_and_b32_e32 v11, 0xffff0000, v33
	v_pk_add_f32 v[10:11], v[222:223], v[10:11] neg_lo:[0,1] neg_hi:[0,1]
	v_cvt_pk_bf16_f32 v37, v10, v11
	v_add_u32_e32 v10, 0x400, v170
	s_waitcnt lgkmcnt(13)
	v_cvt_pk_bf16_f32 v10, v212, v213
	v_lshlrev_b32_e32 v14, 16, v10
	v_and_b32_e32 v15, 0xffff0000, v10
	v_pk_add_f32 v[12:13], v[212:213], v[14:15] neg_lo:[0,1] neg_hi:[0,1]
	s_waitcnt lgkmcnt(12)
	v_cvt_pk_bf16_f32 v11, v224, v225
	v_cvt_pk_bf16_f32 v14, v12, v13
	v_lshlrev_b32_e32 v12, 16, v11
	v_and_b32_e32 v13, 0xffff0000, v11
	v_pk_add_f32 v[12:13], v[224:225], v[12:13] neg_lo:[0,1] neg_hi:[0,1]
	s_nop 0
	v_cvt_pk_bf16_f32 v15, v12, v13
	s_waitcnt lgkmcnt(11)
	v_cvt_pk_bf16_f32 v12, v226, v227
	v_lshlrev_b32_e32 v16, 16, v12
	v_and_b32_e32 v17, 0xffff0000, v12
	s_waitcnt lgkmcnt(9)
	v_cvt_pk_bf16_f32 v13, v196, v197
	v_pk_add_f32 v[16:17], v[226:227], v[16:17] neg_lo:[0,1] neg_hi:[0,1]
	v_lshlrev_b32_e32 v18, 16, v13
	v_and_b32_e32 v19, 0xffff0000, v13
	v_pk_add_f32 v[18:19], v[196:197], v[18:19] neg_lo:[0,1] neg_hi:[0,1]
	v_cvt_pk_bf16_f32 v16, v16, v17
	v_cvt_pk_bf16_f32 v17, v18, v19
	v_mfma_f32_16x16x32_bf16 v[18:21], v[30:33], v[10:13], 0
	s_nop 0
	v_mfma_f32_16x16x32_bf16 v[18:21], v[30:33], v[14:17], v[18:21]
	v_mfma_f32_16x16x32_bf16 v[26:29], v[34:37], v[10:13], v[18:21]
	s_nop 6
	s_waitcnt lgkmcnt(7)
	v_cvt_pk_bf16_f32 v18, v198, v199
	v_lshlrev_b32_e32 v22, 16, v18
	v_and_b32_e32 v23, 0xffff0000, v18
	v_pk_add_f32 v[20:21], v[198:199], v[22:23] neg_lo:[0,1] neg_hi:[0,1]
	s_waitcnt lgkmcnt(5)
	v_cvt_pk_bf16_f32 v19, v202, v203
	v_cvt_pk_bf16_f32 v22, v20, v21
	v_lshlrev_b32_e32 v20, 16, v19
	v_and_b32_e32 v21, 0xffff0000, v19
	v_pk_add_f32 v[20:21], v[202:203], v[20:21] neg_lo:[0,1] neg_hi:[0,1]
	ds_read_b32 v57, v181
	v_cvt_pk_bf16_f32 v23, v20, v21
	s_waitcnt lgkmcnt(4)
	v_cvt_pk_bf16_f32 v20, v204, v205
	v_lshlrev_b32_e32 v24, 16, v20
	v_and_b32_e32 v25, 0xffff0000, v20
	s_waitcnt lgkmcnt(2)
	v_cvt_pk_bf16_f32 v21, v206, v207
	v_pk_add_f32 v[24:25], v[204:205], v[24:25] neg_lo:[0,1] neg_hi:[0,1]
	v_lshlrev_b32_e32 v38, 16, v21
	v_and_b32_e32 v39, 0xffff0000, v21
	v_pk_add_f32 v[38:39], v[206:207], v[38:39] neg_lo:[0,1] neg_hi:[0,1]
	v_cvt_pk_bf16_f32 v24, v24, v25
	v_cvt_pk_bf16_f32 v25, v38, v39
	v_mfma_f32_16x16x32_bf16 v[38:41], v[30:33], v[18:21], 0
	s_nop 0
	v_mfma_f32_16x16x32_bf16 v[30:33], v[30:33], v[22:25], v[38:41]
	v_mfma_f32_16x16x32_bf16 v[46:49], v[34:37], v[18:21], v[30:33]
	s_nop 6
	s_waitcnt lgkmcnt(0)
	v_cvt_pk_bf16_f32 v38, v244, v245
	v_lshlrev_b32_e32 v34, 16, v38
	v_and_b32_e32 v35, 0xffff0000, v38
	v_pk_add_f32 v[30:31], v[244:245], v[34:35] neg_lo:[0,1] neg_hi:[0,1]
	v_cvt_pk_bf16_f32 v39, v246, v247
	v_cvt_pk_bf16_f32 v42, v30, v31
	v_lshlrev_b32_e32 v30, 16, v39
	v_and_b32_e32 v31, 0xffff0000, v39
	v_pk_add_f32 v[30:31], v[246:247], v[30:31] neg_lo:[0,1] neg_hi:[0,1]
	s_nop 0
	v_cvt_pk_bf16_f32 v43, v30, v31
	ds_read_b128 v[30:33], v169 offset:144
	s_waitcnt lgkmcnt(0)
	v_cvt_pk_bf16_f32 v40, v30, v31
	v_lshlrev_b32_e32 v34, 16, v40
	v_and_b32_e32 v35, 0xffff0000, v40
	v_pk_add_f32 v[30:31], v[30:31], v[34:35] neg_lo:[0,1] neg_hi:[0,1]
	v_cvt_pk_bf16_f32 v41, v32, v33
	v_cvt_pk_bf16_f32 v44, v30, v31
	v_lshlrev_b32_e32 v30, 16, v41
	v_and_b32_e32 v31, 0xffff0000, v41
	v_pk_add_f32 v[30:31], v[32:33], v[30:31] neg_lo:[0,1] neg_hi:[0,1]
	ds_read_b32 v32, v180
	v_cvt_pk_bf16_f32 v45, v30, v31
	v_add_u32_e32 v30, 0x2200, v170
	ds_read2_b32 v[30:31], v30 offset0:68 offset1:136
	v_add_u32_e32 v34, 0x2400, v170
	ds_read2_b32 v[36:37], v34 offset0:76 offset1:144
	v_add_u32_e32 v34, 0x2600, v170
	ds_read2_b32 v[52:53], v34 offset0:84 offset1:152
	s_waitcnt lgkmcnt(2)
	v_mov_b32_e32 v33, v30
	v_cvt_pk_bf16_f32 v30, v32, v30
	v_lshlrev_b32_e32 v34, 16, v30
	v_and_b32_e32 v35, 0xffff0000, v30
	v_mov_b32_e32 v50, v31
	v_pk_add_f32 v[32:33], v[32:33], v[34:35] neg_lo:[0,1] neg_hi:[0,1]
	s_waitcnt lgkmcnt(1)
	v_cvt_pk_bf16_f32 v31, v31, v36
	v_mov_b32_e32 v51, v36
	v_cvt_pk_bf16_f32 v34, v32, v33
	v_lshlrev_b32_e32 v32, 16, v31
	v_and_b32_e32 v33, 0xffff0000, v31
	v_pk_add_f32 v[32:33], v[50:51], v[32:33] neg_lo:[0,1] neg_hi:[0,1]
	v_mov_b32_e32 v54, v37
	v_cvt_pk_bf16_f32 v35, v32, v33
	s_waitcnt lgkmcnt(0)
	v_cvt_pk_bf16_f32 v32, v37, v52
	v_cvt_pk_bf16_f32 v33, v53, v57
	v_mov_b32_e32 v55, v52
	v_mov_b32_e32 v56, v53
	v_lshlrev_b32_e32 v36, 16, v32
	v_and_b32_e32 v37, 0xffff0000, v32
	v_lshlrev_b32_e32 v50, 16, v33
	v_and_b32_e32 v51, 0xffff0000, v33
	v_pk_add_f32 v[36:37], v[54:55], v[36:37] neg_lo:[0,1] neg_hi:[0,1]
	v_pk_add_f32 v[50:51], v[56:57], v[50:51] neg_lo:[0,1] neg_hi:[0,1]
	v_cvt_pk_bf16_f32 v36, v36, v37
	v_cvt_pk_bf16_f32 v37, v50, v51
	ds_read_b32 v52, v182
	ds_read_b32 v53, v183
	ds_read_b32 v56, v184
	ds_read_b32 v57, v185
	ds_read_b32 v190, v186
	ds_read_b32 v191, v187
	ds_read_b32 v192, v188
	ds_read_b32 v193, v189
	s_waitcnt lgkmcnt(6)
	v_cvt_pk_bf16_f32 v50, v52, v53
	v_lshlrev_b32_e32 v54, 16, v50
	v_and_b32_e32 v55, 0xffff0000, v50
	v_pk_add_f32 v[52:53], v[52:53], v[54:55] neg_lo:[0,1] neg_hi:[0,1]
	s_waitcnt lgkmcnt(4)
	v_cvt_pk_bf16_f32 v51, v56, v57
	v_cvt_pk_bf16_f32 v54, v52, v53
	v_lshlrev_b32_e32 v52, 16, v51
	v_and_b32_e32 v53, 0xffff0000, v51
	v_pk_add_f32 v[52:53], v[56:57], v[52:53] neg_lo:[0,1] neg_hi:[0,1]
	v_mfma_f32_16x16x32_bf16 v[26:29], v[38:41], v[30:33], v[26:29]
	v_cvt_pk_bf16_f32 v55, v52, v53
	s_waitcnt lgkmcnt(2)
	v_cvt_pk_bf16_f32 v52, v190, v191
	s_waitcnt lgkmcnt(0)
	v_cvt_pk_bf16_f32 v53, v192, v193
	v_lshlrev_b32_e32 v56, 16, v52
	v_and_b32_e32 v57, 0xffff0000, v52
	v_mfma_f32_16x16x32_bf16 v[46:49], v[38:41], v[50:53], v[46:49]
	v_add_f32_e64 v56, v190, -v56
	v_add_f32_e64 v57, v191, -v57
	v_lshlrev_b32_e32 v190, 16, v53
	v_and_b32_e32 v191, 0xffff0000, v53
	v_pk_add_f32 v[190:191], v[192:193], v[190:191] neg_lo:[0,1] neg_hi:[0,1]
	v_cvt_pk_bf16_f32 v56, v56, v57
	v_cvt_pk_bf16_f32 v57, v190, v191
	v_mfma_f32_16x16x32_bf16 v[26:29], v[38:41], v[34:37], v[26:29]
	s_nop 0
	v_mfma_f32_16x16x32_bf16 v[38:41], v[38:41], v[54:57], v[46:49]
	v_mfma_f32_16x16x32_bf16 v[26:29], v[42:45], v[30:33], v[26:29]
	s_nop 1
	v_mov_b32_e32 v46, 0
	v_mov_b32_e32 v47, 0
	v_mov_b32_e32 v48, 0
	v_mfma_f32_16x16x32_bf16 v[38:41], v[42:45], v[50:53], v[38:41]
	v_mov_b32_e32 v42, 0
	v_mov_b32_e32 v43, 0
	v_mov_b32_e32 v44, 0
	v_mov_b32_e32 v45, 0
	v_mov_b32_e32 v49, 0
	s_cbranch_scc1 .LBB0_655
	ds_read_b128 v[42:45], v95
	ds_read_b128 v[46:49], v95 offset:16
	s_waitcnt lgkmcnt(1)
	v_cvt_pk_bf16_f32 v190, v42, v43
	v_lshlrev_b32_e32 v192, 16, v190
	v_and_b32_e32 v193, 0xffff0000, v190
	v_cvt_pk_bf16_f32 v191, v44, v45
	v_pk_add_f32 v[42:43], v[42:43], v[192:193] neg_lo:[0,1] neg_hi:[0,1]
	v_lshlrev_b32_e32 v192, 16, v191
	v_and_b32_e32 v193, 0xffff0000, v191
	v_pk_add_f32 v[44:45], v[44:45], v[192:193] neg_lo:[0,1] neg_hi:[0,1]
	s_waitcnt lgkmcnt(0)
	v_cvt_pk_bf16_f32 v192, v46, v47
	v_cvt_pk_bf16_f32 v193, v48, v49
	v_cvt_pk_bf16_f32 v42, v42, v43
	v_cvt_pk_bf16_f32 v43, v44, v45
	v_lshlrev_b32_e32 v44, 16, v192
	v_and_b32_e32 v45, 0xffff0000, v192
	v_pk_add_f32 v[44:45], v[46:47], v[44:45] neg_lo:[0,1] neg_hi:[0,1]
	v_lshlrev_b32_e32 v46, 16, v193
	v_and_b32_e32 v47, 0xffff0000, v193
	v_pk_add_f32 v[46:47], v[48:49], v[46:47] neg_lo:[0,1] neg_hi:[0,1]
	v_cvt_pk_bf16_f32 v44, v44, v45
	v_cvt_pk_bf16_f32 v45, v46, v47
	v_mfma_f32_16x16x32_bf16 v[46:49], v[190:193], v[10:13], 0
	v_mfma_f32_16x16x32_bf16 v[14:17], v[190:193], v[14:17], v[46:49]
	v_mfma_f32_16x16x32_bf16 v[10:13], v[42:45], v[10:13], v[14:17]
	v_mfma_f32_16x16x32_bf16 v[14:17], v[190:193], v[18:21], 0
	v_mfma_f32_16x16x32_bf16 v[14:17], v[190:193], v[22:25], v[14:17]
	v_mfma_f32_16x16x32_bf16 v[14:17], v[42:45], v[18:21], v[14:17]
	ds_read_b128 v[18:21], v95 offset:128
	ds_read_b128 v[42:45], v95 offset:144
	s_waitcnt lgkmcnt(1)
	v_cvt_pk_bf16_f32 v22, v18, v19
	v_lshlrev_b32_e32 v24, 16, v22
	v_and_b32_e32 v25, 0xffff0000, v22
	v_cvt_pk_bf16_f32 v23, v20, v21
	v_pk_add_f32 v[18:19], v[18:19], v[24:25] neg_lo:[0,1] neg_hi:[0,1]
	v_lshlrev_b32_e32 v24, 16, v23
	v_and_b32_e32 v25, 0xffff0000, v23
	v_pk_add_f32 v[20:21], v[20:21], v[24:25] neg_lo:[0,1] neg_hi:[0,1]
	s_waitcnt lgkmcnt(0)
	v_cvt_pk_bf16_f32 v24, v42, v43
	v_cvt_pk_bf16_f32 v25, v44, v45
	v_cvt_pk_bf16_f32 v18, v18, v19
	v_cvt_pk_bf16_f32 v19, v20, v21
	v_lshlrev_b32_e32 v20, 16, v24
	v_and_b32_e32 v21, 0xffff0000, v24
	v_mfma_f32_16x16x32_bf16 v[10:13], v[22:25], v[30:33], v[10:13]
	v_add_f32_e64 v20, v42, -v20
	v_add_f32_e64 v21, v43, -v21
	v_lshlrev_b32_e32 v42, 16, v25
	v_and_b32_e32 v43, 0xffff0000, v25
	v_pk_add_f32 v[42:43], v[44:45], v[42:43] neg_lo:[0,1] neg_hi:[0,1]
	v_cvt_pk_bf16_f32 v20, v20, v21
	v_cvt_pk_bf16_f32 v21, v42, v43
	v_mfma_f32_16x16x32_bf16 v[10:13], v[22:25], v[34:37], v[10:13]
	s_nop 0
	v_mfma_f32_16x16x32_bf16 v[42:45], v[18:21], v[30:33], v[10:13]
	v_mfma_f32_16x16x32_bf16 v[10:13], v[22:25], v[50:53], v[14:17]
	v_mfma_f32_16x16x32_bf16 v[10:13], v[22:25], v[54:57], v[10:13]
	v_mfma_f32_16x16x32_bf16 v[46:49], v[18:21], v[50:53], v[10:13]
